# conv tile fill de-serialised: 16 row-group loads issued together with one wait instead of load-wait-write per row group
# speedup vs baseline: 1.0023x; 1.0023x over previous
; #define LAS __attribute__((address_space(3)))
; __device__ __forceinline__ void conv_phase(LAS unsigned char* lds, const bf16_t* U, bf16_t* C, const float* wdw, const float* bdw, const float* lng, const float* lnb,
;                                            int first, int stride, int end, int tid, int wave, int lane) {
;     ...
;         for (int idx = tid; idx < ROWS * 128; idx += NTHREADS) {
;             const int row = idx >> 7, ch = idx & 127;
;             u32x4 v = (u32x4){0u, 0u, 0u, 0u};
;             if (tin + row - (CW - 1) >= 0) v = *(const u32x4*)(U + (size_t)(t0 + row - (CW - 1)) * D + ch * 8);
;             *(LAS u32x4*)(lds + row * 2048 + ch * 16) = v;
;         }
.LBB0_90:
	v_lshlrev_b32_e32 v141, 5, v140
	s_and_saveexec_b64 s[4:5], vcc
	s_cbranch_execz .LBB0_89
	v_ashrrev_i32_e32 v0, 31, v141
	v_lshrrev_b32_e32 v0, 20, v0
	v_add_u32_e32 v0, v141, v0
	v_and_b32_e32 v0, 0xfffff000, v0
	v_sub_u32_e32 v0, v0, v141
	v_add_u32_e32 v4, 29, v0
	v_subrev_u32_e32 v5, 30, v141
	v_lshrrev_b32_e32 v6, 7, v132
	v_add_u32_e32 v0, v5, v6
	v_ashrrev_i32_e32 v1, 31, v0
	v_lshl_add_u32 v2, v6, 11, v135
	v_lshlrev_b64 v[0:1], 11, v[0:1]
	v_add_u32_e32 v3, 0x10000, v2
	s_mov_b64 s[28:29], 0x2000
	v_lshl_add_u64 v[0:1], v[94:95], 0, v[0:1]
	v_add_u32_e32 v7, 0, v6
	v_cmp_gt_i32_e64 s[40:41], v7, v4
	v_mov_b32_e32 v8, 0
	v_mov_b32_e32 v9, 0
	v_mov_b32_e32 v10, 0
	v_mov_b32_e32 v11, 0
	s_and_saveexec_b64 s[30:31], s[40:41]
	global_load_dwordx4 v[8:11], v[0:1], off
	s_mov_b64 exec, s[30:31]
	v_lshl_add_u64 v[0:1], v[0:1], 0, s[28:29]
	v_add_u32_e32 v7, 4, v6
	v_cmp_gt_i32_e64 s[40:41], v7, v4
	v_mov_b32_e32 v12, 0
	v_mov_b32_e32 v13, 0
	v_mov_b32_e32 v14, 0
	v_mov_b32_e32 v15, 0
	s_and_saveexec_b64 s[30:31], s[40:41]
	global_load_dwordx4 v[12:15], v[0:1], off
	s_mov_b64 exec, s[30:31]
	v_lshl_add_u64 v[0:1], v[0:1], 0, s[28:29]
	v_add_u32_e32 v7, 8, v6
	v_cmp_gt_i32_e64 s[40:41], v7, v4
	v_mov_b32_e32 v16, 0
	v_mov_b32_e32 v17, 0
	v_mov_b32_e32 v18, 0
	v_mov_b32_e32 v19, 0
	s_and_saveexec_b64 s[30:31], s[40:41]
	global_load_dwordx4 v[16:19], v[0:1], off
	s_mov_b64 exec, s[30:31]
	v_lshl_add_u64 v[0:1], v[0:1], 0, s[28:29]
	v_add_u32_e32 v7, 12, v6
	v_cmp_gt_i32_e64 s[40:41], v7, v4
	v_mov_b32_e32 v20, 0
	v_mov_b32_e32 v21, 0
	v_mov_b32_e32 v22, 0
	v_mov_b32_e32 v23, 0
	s_and_saveexec_b64 s[30:31], s[40:41]
	global_load_dwordx4 v[20:23], v[0:1], off
	s_mov_b64 exec, s[30:31]
	v_lshl_add_u64 v[0:1], v[0:1], 0, s[28:29]
	v_add_u32_e32 v7, 16, v6
	v_cmp_gt_i32_e64 s[40:41], v7, v4
	v_mov_b32_e32 v24, 0
	v_mov_b32_e32 v25, 0
	v_mov_b32_e32 v26, 0
	v_mov_b32_e32 v27, 0
	s_and_saveexec_b64 s[30:31], s[40:41]
	global_load_dwordx4 v[24:27], v[0:1], off
	s_mov_b64 exec, s[30:31]
	v_lshl_add_u64 v[0:1], v[0:1], 0, s[28:29]
	v_add_u32_e32 v7, 20, v6
	v_cmp_gt_i32_e64 s[40:41], v7, v4
	v_mov_b32_e32 v28, 0
	v_mov_b32_e32 v29, 0
	v_mov_b32_e32 v30, 0
	v_mov_b32_e32 v31, 0
	s_and_saveexec_b64 s[30:31], s[40:41]
	global_load_dwordx4 v[28:31], v[0:1], off
	s_mov_b64 exec, s[30:31]
	v_lshl_add_u64 v[0:1], v[0:1], 0, s[28:29]
	v_add_u32_e32 v7, 24, v6
	v_cmp_gt_i32_e64 s[40:41], v7, v4
	v_mov_b32_e32 v32, 0
	v_mov_b32_e32 v33, 0
	v_mov_b32_e32 v34, 0
	v_mov_b32_e32 v35, 0
	s_and_saveexec_b64 s[30:31], s[40:41]
	global_load_dwordx4 v[32:35], v[0:1], off
	s_mov_b64 exec, s[30:31]
	v_lshl_add_u64 v[0:1], v[0:1], 0, s[28:29]
	v_add_u32_e32 v7, 28, v6
	v_cmp_gt_i32_e64 s[40:41], v7, v4
	v_mov_b32_e32 v36, 0
	v_mov_b32_e32 v37, 0
	v_mov_b32_e32 v38, 0
	v_mov_b32_e32 v39, 0
	s_and_saveexec_b64 s[30:31], s[40:41]
	global_load_dwordx4 v[36:39], v[0:1], off
	s_mov_b64 exec, s[30:31]
	v_lshl_add_u64 v[0:1], v[0:1], 0, s[28:29]
	v_add_u32_e32 v7, 32, v6
	v_cmp_gt_i32_e64 s[40:41], v7, v4
	v_mov_b32_e32 v40, 0
	v_mov_b32_e32 v41, 0
	v_mov_b32_e32 v42, 0
	v_mov_b32_e32 v43, 0
	s_and_saveexec_b64 s[30:31], s[40:41]
	global_load_dwordx4 v[40:43], v[0:1], off
	s_mov_b64 exec, s[30:31]
	v_lshl_add_u64 v[0:1], v[0:1], 0, s[28:29]
	v_add_u32_e32 v7, 36, v6
	v_cmp_gt_i32_e64 s[40:41], v7, v4
	v_mov_b32_e32 v44, 0
	v_mov_b32_e32 v45, 0
	v_mov_b32_e32 v46, 0
	v_mov_b32_e32 v47, 0
	s_and_saveexec_b64 s[30:31], s[40:41]
	global_load_dwordx4 v[44:47], v[0:1], off
	s_mov_b64 exec, s[30:31]
	v_lshl_add_u64 v[0:1], v[0:1], 0, s[28:29]
	v_add_u32_e32 v7, 40, v6
	v_cmp_gt_i32_e64 s[40:41], v7, v4
	v_mov_b32_e32 v48, 0
	v_mov_b32_e32 v49, 0
	v_mov_b32_e32 v50, 0
	v_mov_b32_e32 v51, 0
	s_and_saveexec_b64 s[30:31], s[40:41]
	global_load_dwordx4 v[48:51], v[0:1], off
	s_mov_b64 exec, s[30:31]
	v_lshl_add_u64 v[0:1], v[0:1], 0, s[28:29]
	v_add_u32_e32 v7, 44, v6
	v_cmp_gt_i32_e64 s[40:41], v7, v4
	v_mov_b32_e32 v52, 0
	v_mov_b32_e32 v53, 0
	v_mov_b32_e32 v54, 0
	v_mov_b32_e32 v55, 0
	s_and_saveexec_b64 s[30:31], s[40:41]
	global_load_dwordx4 v[52:55], v[0:1], off
	s_mov_b64 exec, s[30:31]
	v_lshl_add_u64 v[0:1], v[0:1], 0, s[28:29]
	v_add_u32_e32 v7, 48, v6
	v_cmp_gt_i32_e64 s[40:41], v7, v4
	v_mov_b32_e32 v56, 0
	v_mov_b32_e32 v57, 0
	v_mov_b32_e32 v58, 0
	v_mov_b32_e32 v59, 0
	s_and_saveexec_b64 s[30:31], s[40:41]
	global_load_dwordx4 v[56:59], v[0:1], off
	s_mov_b64 exec, s[30:31]
	v_lshl_add_u64 v[0:1], v[0:1], 0, s[28:29]
	v_add_u32_e32 v7, 52, v6
	v_cmp_gt_i32_e64 s[40:41], v7, v4
	v_mov_b32_e32 v60, 0
	v_mov_b32_e32 v61, 0
	v_mov_b32_e32 v62, 0
	v_mov_b32_e32 v63, 0
	s_and_saveexec_b64 s[30:31], s[40:41]
	global_load_dwordx4 v[60:63], v[0:1], off
	s_mov_b64 exec, s[30:31]
	v_lshl_add_u64 v[0:1], v[0:1], 0, s[28:29]
	v_add_u32_e32 v7, 56, v6
	v_cmp_gt_i32_e64 s[40:41], v7, v4
	v_mov_b32_e32 v64, 0
	v_mov_b32_e32 v65, 0
	v_mov_b32_e32 v66, 0
	v_mov_b32_e32 v67, 0
	s_and_saveexec_b64 s[30:31], s[40:41]
	global_load_dwordx4 v[64:67], v[0:1], off
	s_mov_b64 exec, s[30:31]
	v_lshl_add_u64 v[0:1], v[0:1], 0, s[28:29]
	v_add_u32_e32 v7, 60, v6
	v_cmp_gt_i32_e64 s[40:41], v7, v4
	v_mov_b32_e32 v68, 0
	v_mov_b32_e32 v69, 0
	v_mov_b32_e32 v70, 0
	v_mov_b32_e32 v71, 0
	v_cmp_gt_i32_e64 s[30:31], 2, v6
	s_nop 1
	s_and_b64 s[40:41], s[40:41], s[30:31]
	s_and_saveexec_b64 s[30:31], s[40:41]
	global_load_dwordx4 v[68:71], v[0:1], off
	s_mov_b64 exec, s[30:31]
	s_waitcnt vmcnt(0)
	ds_write_b128 v2, v[8:11]
	ds_write_b128 v2, v[12:15] offset:8192
	ds_write_b128 v2, v[16:19] offset:16384
	ds_write_b128 v2, v[20:23] offset:24576
	ds_write_b128 v2, v[24:27] offset:32768
	ds_write_b128 v2, v[28:31] offset:40960
	ds_write_b128 v2, v[32:35] offset:49152
	ds_write_b128 v2, v[36:39] offset:57344
	ds_write_b128 v3, v[40:43]
	ds_write_b128 v3, v[44:47] offset:8192
	ds_write_b128 v3, v[48:51] offset:16384
	ds_write_b128 v3, v[52:55] offset:24576
	ds_write_b128 v3, v[56:59] offset:32768
	ds_write_b128 v3, v[60:63] offset:40960
	ds_write_b128 v3, v[64:67] offset:49152
	v_cmp_gt_i32_e64 s[40:41], 2, v6
	s_nop 1
	s_and_saveexec_b64 s[30:31], s[40:41]
	ds_write_b128 v3, v[68:71] offset:57344
	s_mov_b64 exec, s[30:31]
	s_branch .LBB0_89
